# phase0 silu(cond) staging: 6 serialized s_load+load+wait iterations replaced by 6 loads issued together (same math)
# speedup vs baseline: 1.0565x; 1.0005x over previous
.LBB0_5:
	s_or_b64 exec, exec, s[0:1]
	s_mov_b64 s[8:9], s[24:25]
	v_mbcnt_lo_u32_b32 v25, -1, 0
	v_mbcnt_hi_u32_b32 v25, -1, v25
	s_load_dwordx2 s[4:5], s[8:9], 0xc0
	s_and_b32 s3, s6, 0xffffffc0
	v_or_b32_e32 v22, s3, v25
	s_movk_i32 s0, 0xc00
	v_readfirstlane_b32 s16, v22
	s_waitcnt lgkmcnt(0)
	s_mov_b64 s[6:7], s[4:5]
	v_cmp_gt_i32_e32 vcc, s0, v22
	s_and_saveexec_b64 s[10:11], vcc
	s_cbranch_execz .LBB0_12
	v_ashrrev_i32_e32 v23, 31, v22
	s_load_dwordx2 s[22:23], s[8:9], 0x8
	s_load_dwordx2 s[14:15], s[8:9], 0x18
	v_lshlrev_b32_e32 v2, 2, v22
	v_lshl_add_u32 v8, v22, 2, 0
	s_movk_i32 s17, 0x7ff
	s_mov_b64 s[12:13], exec
	s_mov_b32 s18, 0xbfb8aa3b
	s_mov_b32 s19, 0x42ce8ed0
	s_mov_b32 s20, 0xc2b17218
	v_mov_b32_e32 v9, 0x7f800000
	s_waitcnt lgkmcnt(0)
	global_load_dword v30, v2, s[22:23]
	global_load_dword v31, v2, s[22:23] offset:2048
	s_add_u32 s22, s22, 0x1000
	s_addc_u32 s23, s23, 0
	global_load_dword v32, v2, s[22:23]
	global_load_dword v33, v2, s[22:23] offset:2048
	global_load_dword v34, v2, s[14:15]
	global_load_dword v35, v2, s[14:15] offset:2048
	s_waitcnt vmcnt(5)
	v_mul_f32_e32 v6, 0xbfb8aa3b, v30
	v_rndne_f32_e32 v7, v6
	v_fma_f32 v11, v30, s18, -v6
	v_sub_f32_e32 v6, v6, v7
	v_fmac_f32_e32 v11, 0xb2a5705f, v30
	v_add_f32_e32 v6, v6, v11
	v_cvt_i32_f32_e32 v7, v7
	v_exp_f32_e32 v6, v6
	v_cmp_nlt_f32_e64 s[0:1], s19, v30
	s_nop 0
	v_ldexp_f32 v6, v6, v7
	v_cndmask_b32_e64 v6, 0, v6, s[0:1]
	v_cmp_ngt_f32_e64 s[0:1], s20, v30
	s_nop 1
	v_cndmask_b32_e64 v6, v9, v6, s[0:1]
	v_add_f32_e32 v6, 1.0, v6
	v_div_scale_f32 v7, s[0:1], v6, v6, v30
	v_rcp_f32_e32 v10, v7
	v_div_scale_f32 v12, vcc, v30, v6, v30
	v_fma_f32 v13, -v7, v10, 1.0
	v_fmac_f32_e32 v10, v13, v10
	v_mul_f32_e32 v13, v12, v10
	v_fma_f32 v14, -v7, v13, v12
	v_fmac_f32_e32 v13, v14, v10
	v_fma_f32 v7, -v7, v13, v12
	v_div_fmas_f32 v7, v7, v10, v13
	v_div_fixup_f32 v4, v7, v6, v30
	ds_write_b32 v8, v4
	s_waitcnt vmcnt(4)
	v_mul_f32_e32 v6, 0xbfb8aa3b, v31
	v_rndne_f32_e32 v7, v6
	v_fma_f32 v11, v31, s18, -v6
	v_sub_f32_e32 v6, v6, v7
	v_fmac_f32_e32 v11, 0xb2a5705f, v31
	v_add_f32_e32 v6, v6, v11
	v_cvt_i32_f32_e32 v7, v7
	v_exp_f32_e32 v6, v6
	v_cmp_nlt_f32_e64 s[0:1], s19, v31
	s_nop 0
	v_ldexp_f32 v6, v6, v7
	v_cndmask_b32_e64 v6, 0, v6, s[0:1]
	v_cmp_ngt_f32_e64 s[0:1], s20, v31
	s_nop 1
	v_cndmask_b32_e64 v6, v9, v6, s[0:1]
	v_add_f32_e32 v6, 1.0, v6
	v_div_scale_f32 v7, s[0:1], v6, v6, v31
	v_rcp_f32_e32 v10, v7
	v_div_scale_f32 v12, vcc, v31, v6, v31
	v_fma_f32 v13, -v7, v10, 1.0
	v_fmac_f32_e32 v10, v13, v10
	v_mul_f32_e32 v13, v12, v10
	v_fma_f32 v14, -v7, v13, v12
	v_fmac_f32_e32 v13, v14, v10
	v_fma_f32 v7, -v7, v13, v12
	v_div_fmas_f32 v7, v7, v10, v13
	v_div_fixup_f32 v4, v7, v6, v31
	ds_write_b32 v8, v4 offset:2048
	s_waitcnt vmcnt(3)
	v_mul_f32_e32 v6, 0xbfb8aa3b, v32
	v_rndne_f32_e32 v7, v6
	v_fma_f32 v11, v32, s18, -v6
	v_sub_f32_e32 v6, v6, v7
	v_fmac_f32_e32 v11, 0xb2a5705f, v32
	v_add_f32_e32 v6, v6, v11
	v_cvt_i32_f32_e32 v7, v7
	v_exp_f32_e32 v6, v6
	v_cmp_nlt_f32_e64 s[0:1], s19, v32
	s_nop 0
	v_ldexp_f32 v6, v6, v7
	v_cndmask_b32_e64 v6, 0, v6, s[0:1]
	v_cmp_ngt_f32_e64 s[0:1], s20, v32
	s_nop 1
	v_cndmask_b32_e64 v6, v9, v6, s[0:1]
	v_add_f32_e32 v6, 1.0, v6
	v_div_scale_f32 v7, s[0:1], v6, v6, v32
	v_rcp_f32_e32 v10, v7
	v_div_scale_f32 v12, vcc, v32, v6, v32
	v_fma_f32 v13, -v7, v10, 1.0
	v_fmac_f32_e32 v10, v13, v10
	v_mul_f32_e32 v13, v12, v10
	v_fma_f32 v14, -v7, v13, v12
	v_fmac_f32_e32 v13, v14, v10
	v_fma_f32 v7, -v7, v13, v12
	v_div_fmas_f32 v7, v7, v10, v13
	v_div_fixup_f32 v4, v7, v6, v32
	ds_write_b32 v8, v4 offset:4096
	s_waitcnt vmcnt(2)
	v_mul_f32_e32 v6, 0xbfb8aa3b, v33
	v_rndne_f32_e32 v7, v6
	v_fma_f32 v11, v33, s18, -v6
	v_sub_f32_e32 v6, v6, v7
	v_fmac_f32_e32 v11, 0xb2a5705f, v33
	v_add_f32_e32 v6, v6, v11
	v_cvt_i32_f32_e32 v7, v7
	v_exp_f32_e32 v6, v6
	v_cmp_nlt_f32_e64 s[0:1], s19, v33
	s_nop 0
	v_ldexp_f32 v6, v6, v7
	v_cndmask_b32_e64 v6, 0, v6, s[0:1]
	v_cmp_ngt_f32_e64 s[0:1], s20, v33
	s_nop 1
	v_cndmask_b32_e64 v6, v9, v6, s[0:1]
	v_add_f32_e32 v6, 1.0, v6
	v_div_scale_f32 v7, s[0:1], v6, v6, v33
	v_rcp_f32_e32 v10, v7
	v_div_scale_f32 v12, vcc, v33, v6, v33
	v_fma_f32 v13, -v7, v10, 1.0
	v_fmac_f32_e32 v10, v13, v10
	v_mul_f32_e32 v13, v12, v10
	v_fma_f32 v14, -v7, v13, v12
	v_fmac_f32_e32 v13, v14, v10
	v_fma_f32 v7, -v7, v13, v12
	v_div_fmas_f32 v7, v7, v10, v13
	v_div_fixup_f32 v4, v7, v6, v33
	ds_write_b32 v8, v4 offset:6144
	s_waitcnt vmcnt(1)
	v_mul_f32_e32 v6, 0xbfb8aa3b, v34
	v_rndne_f32_e32 v7, v6
	v_fma_f32 v11, v34, s18, -v6
	v_sub_f32_e32 v6, v6, v7
	v_fmac_f32_e32 v11, 0xb2a5705f, v34
	v_add_f32_e32 v6, v6, v11
	v_cvt_i32_f32_e32 v7, v7
	v_exp_f32_e32 v6, v6
	v_cmp_nlt_f32_e64 s[0:1], s19, v34
	s_nop 0
	v_ldexp_f32 v6, v6, v7
	v_cndmask_b32_e64 v6, 0, v6, s[0:1]
	v_cmp_ngt_f32_e64 s[0:1], s20, v34
	s_nop 1
	v_cndmask_b32_e64 v6, v9, v6, s[0:1]
	v_add_f32_e32 v6, 1.0, v6
	v_div_scale_f32 v7, s[0:1], v6, v6, v34
	v_rcp_f32_e32 v10, v7
	v_div_scale_f32 v12, vcc, v34, v6, v34
	v_fma_f32 v13, -v7, v10, 1.0
	v_fmac_f32_e32 v10, v13, v10
	v_mul_f32_e32 v13, v12, v10
	v_fma_f32 v14, -v7, v13, v12
	v_fmac_f32_e32 v13, v14, v10
	v_fma_f32 v7, -v7, v13, v12
	v_div_fmas_f32 v7, v7, v10, v13
	v_div_fixup_f32 v4, v7, v6, v34
	ds_write_b32 v8, v4 offset:8192
	s_waitcnt vmcnt(0)
	v_mul_f32_e32 v6, 0xbfb8aa3b, v35
	v_rndne_f32_e32 v7, v6
	v_fma_f32 v11, v35, s18, -v6
	v_sub_f32_e32 v6, v6, v7
	v_fmac_f32_e32 v11, 0xb2a5705f, v35
	v_add_f32_e32 v6, v6, v11
	v_cvt_i32_f32_e32 v7, v7
	v_exp_f32_e32 v6, v6
	v_cmp_nlt_f32_e64 s[0:1], s19, v35
	s_nop 0
	v_ldexp_f32 v6, v6, v7
	v_cndmask_b32_e64 v6, 0, v6, s[0:1]
	v_cmp_ngt_f32_e64 s[0:1], s20, v35
	s_nop 1
	v_cndmask_b32_e64 v6, v9, v6, s[0:1]
	v_add_f32_e32 v6, 1.0, v6
	v_div_scale_f32 v7, s[0:1], v6, v6, v35
	v_rcp_f32_e32 v10, v7
	v_div_scale_f32 v12, vcc, v35, v6, v35
	v_fma_f32 v13, -v7, v10, 1.0
	v_fmac_f32_e32 v10, v13, v10
	v_mul_f32_e32 v13, v12, v10
	v_fma_f32 v14, -v7, v13, v12
	v_fmac_f32_e32 v13, v14, v10
	v_fma_f32 v7, -v7, v13, v12
	v_div_fmas_f32 v7, v7, v10, v13
	v_div_fixup_f32 v4, v7, v6, v35
	ds_write_b32 v8, v4 offset:10240
